# mixer A: exponent arguments for adjacent accumulator registers formed by one v_pk_fma_f32 (35 pairs), scheduled one instruction ahead of the first v_exp
# baseline (speedup 1.0000x reference)
; __device__ __forceinline__ void attnA_unit(LAS unsigned char* lds, const Args& A, int unit) {
;     ...
;                 float mx = fmaxf(mxp[0], mxp[1]);
;                 mx = fmaxf(mx, __shfl_xor(mx, 32));
;                 float lsp[2] = {0.f, 0.f};
; #pragma unroll
;                 for (int kt = 0; kt < 5; ++kt)
; #pragma unroll
;                     for (int i = 0; i < 16; ++i) { const float p = __builtin_amdgcn_exp2f(S[kt][i] - mx); S[kt][i] = p; lsp[i & 1] += p; }
.LmixA_join:
	v_and_b32_e32 v2, 64, v217
	v_xor_b32_e32 v1, 32, v217
	v_add_u32_e32 v2, 64, v2
	v_cmp_lt_i32_e32 vcc, v1, v2
	v_lshlrev_b32_e32 v32, v206, v164
	s_nop 0
	v_cndmask_b32_e32 v1, v217, v1, vcc
	v_lshlrev_b32_e32 v238, 2, v1
	ds_bpermute_b32 v1, v238, v0
	s_waitcnt lgkmcnt(0)
	v_max_f32_e32 v1, v1, v1
	v_max_f32_e32 v229, v0, v1
	v_mul_f32_e32 v229, 0x3e38aa3b, v229
	v_mov_b32_e32 v252, 0x3e38aa3b
	s_nop 0
	v_pk_fma_f32 v[186:187], v[76:77], v[252:253], v[228:229] op_sel:[0,0,1] op_sel_hi:[1,0,1] neg_lo:[0,0,1] neg_hi:[0,0,1]
	s_nop 0
	v_exp_f32_e32 v172, v186
	v_pk_fma_f32 v[188:189], v[78:79], v[252:253], v[228:229] op_sel:[0,0,1] op_sel_hi:[1,0,1] neg_lo:[0,0,1] neg_hi:[0,0,1]
	v_exp_f32_e32 v173, v187
	v_exp_f32_e32 v174, v188
	v_exp_f32_e32 v175, v189
	v_pk_fma_f32 v[186:187], v[48:49], v[252:253], v[228:229] op_sel:[0,0,1] op_sel_hi:[1,0,1] neg_lo:[0,0,1] neg_hi:[0,0,1]
	v_pk_fma_f32 v[248:249], v[72:73], v[252:253], v[228:229] op_sel:[0,0,1] op_sel_hi:[1,0,1] neg_lo:[0,0,1] neg_hi:[0,0,1]
	v_exp_f32_e32 v72, v186
	v_exp_f32_e32 v166, v248
	v_exp_f32_e32 v73, v187
	v_pk_fma_f32 v[188:189], v[50:51], v[252:253], v[228:229] op_sel:[0,0,1] op_sel_hi:[1,0,1] neg_lo:[0,0,1] neg_hi:[0,0,1]
	v_exp_f32_e32 v167, v249
	v_fma_f32 v8, v74, v252, -v229
	v_exp_f32_e32 v74, v188
	v_pk_fma_f32 v[186:187], v[52:53], v[252:253], v[228:229] op_sel:[0,0,1] op_sel_hi:[1,0,1] neg_lo:[0,0,1] neg_hi:[0,0,1]
	v_exp_f32_e32 v75, v189
	v_exp_f32_e32 v76, v186
	v_pk_fma_f32 v[188:189], v[54:55], v[252:253], v[228:229] op_sel:[0,0,1] op_sel_hi:[1,0,1] neg_lo:[0,0,1] neg_hi:[0,0,1]
	v_exp_f32_e32 v77, v187
	v_exp_f32_e32 v78, v188
	v_pk_fma_f32 v[186:187], v[56:57], v[252:253], v[228:229] op_sel:[0,0,1] op_sel_hi:[1,0,1] neg_lo:[0,0,1] neg_hi:[0,0,1]
	v_exp_f32_e32 v79, v189
	v_exp_f32_e32 v62, v186
	v_exp_f32_e32 v63, v187
	v_pk_fma_f32 v[188:189], v[58:59], v[252:253], v[228:229] op_sel:[0,0,1] op_sel_hi:[1,0,1] neg_lo:[0,0,1] neg_hi:[0,0,1]
	v_pk_fma_f32 v[248:249], v[66:67], v[252:253], v[228:229] op_sel:[0,0,1] op_sel_hi:[1,0,1] neg_lo:[0,0,1] neg_hi:[0,0,1]
	v_exp_f32_e32 v66, v188
	v_pk_fma_f32 v[186:187], v[64:65], v[252:253], v[228:229] op_sel:[0,0,1] op_sel_hi:[1,0,1] neg_lo:[0,0,1] neg_hi:[0,0,1]
	v_exp_f32_e32 v67, v189
	v_pk_fma_f32 v[250:251], v[60:61], v[252:253], v[228:229] op_sel:[0,0,1] op_sel_hi:[1,0,1] neg_lo:[0,0,1] neg_hi:[0,0,1]
	v_exp_f32_e32 v0, v186
	v_exp_f32_e32 v1, v187
	v_pk_fma_f32 v[188:189], v[68:69], v[252:253], v[228:229] op_sel:[0,0,1] op_sel_hi:[1,0,1] neg_lo:[0,0,1] neg_hi:[0,0,1]
	v_exp_f32_e32 v68, v250
	v_exp_f32_e32 v2, v248
	v_exp_f32_e32 v3, v249
	v_exp_f32_e32 v69, v251
	v_pk_fma_f32 v[186:187], v[168:169], v[252:253], v[228:229] op_sel:[0,0,1] op_sel_hi:[1,0,1] neg_lo:[0,0,1] neg_hi:[0,0,1]
	v_exp_f32_e32 v4, v188
	v_exp_f32_e32 v5, v189
	v_pk_fma_f32 v[248:249], v[70:71], v[252:253], v[228:229] op_sel:[0,0,1] op_sel_hi:[1,0,1] neg_lo:[0,0,1] neg_hi:[0,0,1]
	v_exp_f32_e32 v70, v187
	v_pk_fma_f32 v[188:189], v[208:209], v[252:253], v[228:229] op_sel:[0,0,1] op_sel_hi:[1,0,1] neg_lo:[0,0,1] neg_hi:[0,0,1]
	v_exp_f32_e32 v6, v248
	v_exp_f32_e32 v7, v249
	v_exp_f32_e32 v170, v8
	v_exp_f32_e32 v71, v188
	v_exp_f32_e32 v171, v186
	v_pk_add_f32 v[8:9], v[0:1], 0 op_sel_hi:[1,0]
	v_exp_f32_e32 v54, v189
	v_fma_f32 v10, v33, v252, -v229
	v_pk_add_f32 v[8:9], v[2:3], v[8:9]
	v_exp_f32_e32 v55, v10
	v_pk_fma_f32 v[186:187], v[34:35], v[252:253], v[228:229] op_sel:[0,0,1] op_sel_hi:[1,0,1] neg_lo:[0,0,1] neg_hi:[0,0,1]
	v_pk_add_f32 v[8:9], v[4:5], v[8:9]
	v_exp_f32_e32 v58, v186
	v_pk_add_f32 v[8:9], v[6:7], v[8:9]
	v_exp_f32_e32 v59, v187
	v_pk_fma_f32 v[188:189], v[36:37], v[252:253], v[228:229] op_sel:[0,0,1] op_sel_hi:[1,0,1] neg_lo:[0,0,1] neg_hi:[0,0,1]
	v_pk_add_f32 v[8:9], v[166:167], v[8:9]
	v_exp_f32_e32 v60, v188
	v_pk_add_f32 v[8:9], v[170:171], v[8:9]
	v_exp_f32_e32 v61, v189
	v_pk_fma_f32 v[186:187], v[38:39], v[252:253], v[228:229] op_sel:[0,0,1] op_sel_hi:[1,0,1] neg_lo:[0,0,1] neg_hi:[0,0,1]
	v_pk_add_f32 v[8:9], v[172:173], v[8:9]
	v_exp_f32_e32 v64, v186
	v_pk_add_f32 v[8:9], v[174:175], v[8:9]
	v_exp_f32_e32 v65, v187
	v_pk_fma_f32 v[188:189], v[40:41], v[252:253], v[228:229] op_sel:[0,0,1] op_sel_hi:[1,0,1] neg_lo:[0,0,1] neg_hi:[0,0,1]
	v_pk_add_f32 v[8:9], v[72:73], v[8:9]
	v_exp_f32_e32 v48, v188
	v_pk_add_f32 v[8:9], v[74:75], v[8:9]
	v_exp_f32_e32 v49, v189
	v_pk_fma_f32 v[186:187], v[42:43], v[252:253], v[228:229] op_sel:[0,0,1] op_sel_hi:[1,0,1] neg_lo:[0,0,1] neg_hi:[0,0,1]
	v_pk_add_f32 v[8:9], v[76:77], v[8:9]
	v_exp_f32_e32 v50, v186
	v_pk_add_f32 v[8:9], v[78:79], v[8:9]
	v_exp_f32_e32 v51, v187
	v_pk_fma_f32 v[188:189], v[44:45], v[252:253], v[228:229] op_sel:[0,0,1] op_sel_hi:[1,0,1] neg_lo:[0,0,1] neg_hi:[0,0,1]
	v_pk_add_f32 v[8:9], v[62:63], v[8:9]
	v_exp_f32_e32 v52, v188
	v_pk_add_f32 v[8:9], v[66:67], v[8:9]
	v_exp_f32_e32 v53, v189
	v_pk_fma_f32 v[186:187], v[46:47], v[252:253], v[228:229] op_sel:[0,0,1] op_sel_hi:[1,0,1] neg_lo:[0,0,1] neg_hi:[0,0,1]
	v_pk_add_f32 v[8:9], v[68:69], v[8:9]
	v_exp_f32_e32 v56, v186
	v_pk_add_f32 v[8:9], v[70:71], v[8:9]
	v_exp_f32_e32 v57, v187
	v_pk_fma_f32 v[188:189], v[16:17], v[252:253], v[228:229] op_sel:[0,0,1] op_sel_hi:[1,0,1] neg_lo:[0,0,1] neg_hi:[0,0,1]
	v_pk_add_f32 v[8:9], v[54:55], v[8:9]
	v_exp_f32_e32 v38, v188
	v_exp_f32_e32 v39, v189
	v_pk_fma_f32 v[186:187], v[18:19], v[252:253], v[228:229] op_sel:[0,0,1] op_sel_hi:[1,0,1] neg_lo:[0,0,1] neg_hi:[0,0,1]
	v_pk_add_f32 v[8:9], v[58:59], v[8:9]
	v_exp_f32_e32 v40, v186
	v_pk_add_f32 v[8:9], v[60:61], v[8:9]
	v_exp_f32_e32 v41, v187
; #define LAS __attribute__((address_space(3)))
; #define MFMA32(a, b, c) __builtin_amdgcn_mfma_f32_32x32x16_bf16((a), (b), (c), 0, 0, 0)
; __device__ __forceinline__ s16x4 lds_tr(const LAS unsigned char* p) { return __builtin_bit_cast(s16x4, __builtin_amdgcn_ds_read_tr16_b64_v4i16((LAS v4i16_t*)p)); }
; __device__ __forceinline__ void attnA_unit(LAS unsigned char* lds, const Args& A, int unit) {
;     ...
;                 for (int kt = 0; kt < 5; ++kt)
; #pragma unroll
;                     for (int i = 0; i < 16; ++i) { const float p = __builtin_amdgcn_exp2f(S[kt][i] - mx); S[kt][i] = p; lsp[i & 1] += p; }
;                 float ls = lsp[0] + lsp[1];
;                 ls += __shfl_xor(ls, 32);
;                 f32x16 o0, o1;
; #pragma unroll
;                 for (int i = 0; i < 16; ++i) { o0[i] = 0.f; o1[i] = 0.f; }
;                 const LAS unsigned char* vr0 = vt_l + (rb + 4 * hh + ((lane & 15) >> 2)) * AST + 32 * ((lane >> 4) & 1) + 8 * (lane & 3);
; #pragma unroll
;                 for (int kt = 0; kt < 5; ++kt)
; #pragma unroll
;                     for (int ks = 0; ks < 2; ++ks) {
;                         const bf16x8 pf = pack_frag(S[kt], ks);
;                         const LAS unsigned char* vr = vr0 + (32 * kt + 16 * ks) * AST;
;                         const s16x4 a0 = lds_tr(vr), a1 = lds_tr(vr + 8 * AST), c0 = lds_tr(vr + 64), c1 = lds_tr(vr + 8 * AST + 64);
;                         o0 = MFMA32(__builtin_shufflevector(a0, a1, 0, 1, 2, 3, 4, 5, 6, 7), pf, o0);
;                         o1 = MFMA32(__builtin_shufflevector(c0, c1, 0, 1, 2, 3, 4, 5, 6, 7), pf, o1);
;                     }
	v_pk_fma_f32 v[188:189], v[20:21], v[252:253], v[228:229] op_sel:[0,0,1] op_sel_hi:[1,0,1] neg_lo:[0,0,1] neg_hi:[0,0,1]
	v_pk_add_f32 v[8:9], v[64:65], v[8:9]
	v_exp_f32_e32 v42, v188
	v_pk_add_f32 v[8:9], v[48:49], v[8:9]
	v_exp_f32_e32 v43, v189
	v_pk_fma_f32 v[186:187], v[22:23], v[252:253], v[228:229] op_sel:[0,0,1] op_sel_hi:[1,0,1] neg_lo:[0,0,1] neg_hi:[0,0,1]
	v_pk_add_f32 v[8:9], v[50:51], v[8:9]
	v_exp_f32_e32 v44, v186
	v_pk_add_f32 v[8:9], v[52:53], v[8:9]
	v_exp_f32_e32 v45, v187
	v_pk_add_f32 v[8:9], v[56:57], v[8:9]
	v_pk_fma_f32 v[188:189], v[26:27], v[252:253], v[228:229] op_sel:[0,0,1] op_sel_hi:[1,0,1] neg_lo:[0,0,1] neg_hi:[0,0,1]
	v_pk_add_f32 v[8:9], v[38:39], v[8:9]
	v_cvt_pk_bf16_f32 v16, v0, v1
	v_pk_add_f32 v[8:9], v[40:41], v[8:9]
	v_cvt_pk_bf16_f32 v17, v2, v3
	v_pk_add_f32 v[8:9], v[42:43], v[8:9]
	v_cvt_pk_bf16_f32 v18, v4, v5
	v_pk_fma_f32 v[186:187], v[24:25], v[252:253], v[228:229] op_sel:[0,0,1] op_sel_hi:[1,0,1] neg_lo:[0,0,1] neg_hi:[0,0,1]
	v_pk_add_f32 v[46:47], v[44:45], v[8:9]
	v_exp_f32_e32 v34, v186
	v_exp_f32_e32 v35, v187
	v_exp_f32_e32 v36, v188
	v_add_u32_e32 v8, v180, v163
	v_mad_u64_u32 v[246:247], s[22:23], v8, s88, v[152:153]
	ds_read_b64_tr_b16 v[8:9], v246 offset:59392
	ds_read_b64_tr_b16 v[10:11], v246 offset:60544
	v_cvt_pk_bf16_f32 v19, v6, v7
	v_exp_f32_e32 v37, v189
	v_pk_fma_f32 v[186:187], v[28:29], v[252:253], v[228:229] op_sel:[0,0,1] op_sel_hi:[1,0,1] neg_lo:[0,0,1] neg_hi:[0,0,1]
	ds_read_b64_tr_b16 v[20:21], v246 offset:59456
	ds_read_b64_tr_b16 v[22:23], v246 offset:60608
	s_waitcnt lgkmcnt(2)
	v_mfma_f32_32x32x16_bf16 v[0:15], v[8:11], v[16:19], 0
	v_exp_f32_e32 v164, v186
	ds_read_b64_tr_b16 v[208:209], v246 offset:61696
	ds_read_b64_tr_b16 v[210:211], v246 offset:62848
	v_exp_f32_e32 v165, v187
	v_fma_f32 v24, v30, v252, -v229
	v_exp_f32_e32 v168, v24
	v_cvt_pk_bf16_f32 v242, v166, v167
	s_waitcnt lgkmcnt(2)
	v_mfma_f32_32x32x16_bf16 v[16:31], v[20:23], v[16:19], 0
	v_cvt_pk_bf16_f32 v243, v170, v171
	v_cvt_pk_bf16_f32 v244, v172, v173
	v_cvt_pk_bf16_f32 v245, v174, v175
	ds_read_b64_tr_b16 v[170:171], v246 offset:61760
	ds_read_b64_tr_b16 v[172:173], v246 offset:62912
	v_add_u32_e32 v163, 0xe800, v246
	v_cvt_pk_bf16_f32 v48, v48, v49
	v_cvt_pk_bf16_f32 v49, v50, v51
	s_waitcnt lgkmcnt(2)
	v_mfma_f32_32x32x16_bf16 v[0:15], v[208:211], v[242:245], v[0:15]
	ds_read_b64_tr_b16 v[208:209], v246 offset:64000
	ds_read_b64_tr_b16 v[210:211], v246 offset:65152
	v_cvt_pk_bf16_f32 v50, v52, v53
	v_cvt_pk_bf16_f32 v51, v56, v57
	v_fma_f32 v33, v224, v252, -v229
	v_exp_f32_e32 v169, v33
	v_fma_f32 v33, v223, v252, -v229
	v_cvt_pk_bf16_f32 v38, v38, v39
	s_waitcnt lgkmcnt(2)
	v_mfma_f32_32x32x16_bf16 v[16:31], v[170:173], v[242:245], v[16:31]
	v_cvt_pk_bf16_f32 v170, v72, v73
	v_cvt_pk_bf16_f32 v171, v74, v75
	v_cvt_pk_bf16_f32 v172, v76, v77
	v_cvt_pk_bf16_f32 v173, v78, v79
	ds_read_b64_tr_b16 v[74:75], v246 offset:64064
	ds_read_b64_tr_b16 v[76:77], v246 offset:65216
	v_cvt_pk_bf16_f32 v78, v68, v69
	v_cvt_pk_bf16_f32 v79, v70, v71
	s_waitcnt lgkmcnt(2)
	v_mfma_f32_32x32x16_bf16 v[0:15], v[208:211], v[170:173], v[0:15]
	ds_read_b64_tr_b16 v[208:209], v163 offset:6912
	ds_read_b64_tr_b16 v[210:211], v163 offset:8064
	v_cvt_pk_bf16_f32 v39, v40, v41
	v_cvt_pk_bf16_f32 v40, v42, v43
	v_cvt_pk_bf16_f32 v41, v44, v45
	v_pk_fma_f32 v[186:187], v[226:227], v[252:253], v[228:229] op_sel:[0,0,1] op_sel_hi:[1,0,1] neg_lo:[0,0,1] neg_hi:[0,0,1]
	v_exp_f32_e32 v166, v33
	v_exp_f32_e32 v167, v186
	s_waitcnt lgkmcnt(2)
	v_mfma_f32_32x32x16_bf16 v[16:31], v[74:77], v[170:173], v[16:31]
	v_cvt_pk_bf16_f32 v76, v62, v63
	v_cvt_pk_bf16_f32 v77, v66, v67
	ds_read_b64_tr_b16 v[66:67], v163 offset:6976
	ds_read_b64_tr_b16 v[68:69], v163 offset:8128
	ds_read_b64_tr_b16 v[170:171], v163 offset:9216
	ds_read_b64_tr_b16 v[172:173], v163 offset:10368
	v_fma_f32 v33, v225, v252, -v229
	v_exp_f32_e32 v72, v33
	s_waitcnt lgkmcnt(4)
	v_mfma_f32_32x32x16_bf16 v[0:15], v[208:211], v[76:79], v[0:15]
	v_exp_f32_e32 v73, v187
	v_fma_f32 v33, v228, v252, -v229
	v_exp_f32_e32 v74, v33
	v_fma_f32 v33, v230, v252, -v229
	v_pk_fma_f32 v[186:187], v[232:233], v[252:253], v[228:229] op_sel:[0,0,1] op_sel_hi:[1,0,1] neg_lo:[0,0,1] neg_hi:[0,0,1]
	v_exp_f32_e32 v75, v33
	v_exp_f32_e32 v62, v186
	s_waitcnt lgkmcnt(2)
	v_mfma_f32_32x32x16_bf16 v[16:31], v[66:69], v[76:79], v[16:31]
	v_cvt_pk_bf16_f32 v66, v54, v55
	v_cvt_pk_bf16_f32 v67, v58, v59
	v_cvt_pk_bf16_f32 v68, v60, v61
	v_cvt_pk_bf16_f32 v69, v64, v65
	ds_read_b64_tr_b16 v[58:59], v163 offset:9280
	ds_read_b64_tr_b16 v[60:61], v163 offset:10432
	ds_read_b64_tr_b16 v[76:77], v163 offset:11520
	ds_read_b64_tr_b16 v[78:79], v163 offset:12672
	s_waitcnt lgkmcnt(4)
	v_mfma_f32_32x32x16_bf16 v[0:15], v[170:173], v[66:69], v[0:15]
	v_exp_f32_e32 v63, v187
	v_fma_f32 v33, v231, v252, -v229
	v_pk_fma_f32 v[186:187], v[234:235], v[252:253], v[228:229] op_sel:[0,0,1] op_sel_hi:[1,0,1] neg_lo:[0,0,1] neg_hi:[0,0,1]
	v_exp_f32_e32 v54, v33
	v_exp_f32_e32 v55, v186
	s_waitcnt lgkmcnt(2)
	v_mfma_f32_32x32x16_bf16 v[16:31], v[58:61], v[66:69], v[16:31]
	ds_read_b64_tr_b16 v[56:57], v163 offset:11584
	ds_read_b64_tr_b16 v[58:59], v163 offset:12736
	ds_read_b64_tr_b16 v[64:65], v163 offset:13824
	ds_read_b64_tr_b16 v[66:67], v163 offset:14976
	ds_read_b64_tr_b16 v[42:43], v163 offset:13888
	ds_read_b64_tr_b16 v[44:45], v163 offset:15040
	v_pk_fma_f32 v[188:189], v[236:237], v[252:253], v[228:229] op_sel:[0,0,1] op_sel_hi:[1,0,1] neg_lo:[0,0,1] neg_hi:[0,0,1]
	v_exp_f32_e32 v60, v187
	v_exp_f32_e32 v61, v188
	s_waitcnt lgkmcnt(6)
; #define LAS __attribute__((address_space(3)))
; #define MFMA32(a, b, c) __builtin_amdgcn_mfma_f32_32x32x16_bf16((a), (b), (c), 0, 0, 0)
; __device__ __forceinline__ unsigned cvtpk(float lo, float hi) { f32x2_t v = {lo, hi}; bf16x2_t b = __builtin_convertvector(v, bf16x2_t); return __builtin_bit_cast(unsigned, b); }
; __device__ __forceinline__ s16x4 lds_tr(const LAS unsigned char* p) { return __builtin_bit_cast(s16x4, __builtin_amdgcn_ds_read_tr16_b64_v4i16((LAS v4i16_t*)p)); }
; __device__ __forceinline__ void attnA_unit(LAS unsigned char* lds, const Args& A, int unit) {
;     ...
;                 for (int kt = 0; kt < 5; ++kt)
; #pragma unroll
;                     for (int ks = 0; ks < 2; ++ks) {
;                         const bf16x8 pf = pack_frag(S[kt], ks);
;                         const LAS unsigned char* vr = vr0 + (32 * kt + 16 * ks) * AST;
;                         const s16x4 a0 = lds_tr(vr), a1 = lds_tr(vr + 8 * AST), c0 = lds_tr(vr + 64), c1 = lds_tr(vr + 8 * AST + 64);
;                         o0 = MFMA32(__builtin_shufflevector(a0, a1, 0, 1, 2, 3, 4, 5, 6, 7), pf, o0);
;                         o1 = MFMA32(__builtin_shufflevector(c0, c1, 0, 1, 2, 3, 4, 5, 6, 7), pf, o1);
;                     }
;                 const float inv = 1.0f / ls;
;                 bf16* orow = Qrow + 4 * hh;
; #pragma unroll
;                 for (int g4 = 0; g4 < 4; ++g4) {
;                     u32x2 w; w.x = cvtpk(o0[4 * g4] * inv, o0[4 * g4 + 1] * inv); w.y = cvtpk(o0[4 * g4 + 2] * inv, o0[4 * g4 + 3] * inv); *(u32x2*)(orow + 8 * g4) = w;
;                     u32x2 z; z.x = cvtpk(o1[4 * g4] * inv, o1[4 * g4 + 1] * inv); z.y = cvtpk(o1[4 * g4 + 2] * inv, o1[4 * g4 + 3] * inv); *(u32x2*)(orow + 32 + 8 * g4) = z;
;                 }
;                 if (hh == 0) LSE[(size_t)((g * 4 + b) * 8 + h) * 8192 + pbase + i0 + ql] = mx + __builtin_amdgcn_logf(ls);
	v_mfma_f32_32x32x16_bf16 v[0:15], v[76:79], v[48:51], v[0:15]
	v_pk_fma_f32 v[186:187], v[240:241], v[252:253], v[228:229] op_sel:[0,0,1] op_sel_hi:[1,0,1] neg_lo:[0,0,1] neg_hi:[0,0,1]
	v_exp_f32_e32 v52, v189
	v_exp_f32_e32 v53, v186
	v_fma_f32 v33, v239, v252, -v229
	s_waitcnt lgkmcnt(4)
	v_mfma_f32_32x32x16_bf16 v[16:31], v[56:59], v[48:51], v[16:31]
	v_add_f32_e64 v56, v34, v46
	v_add_f32_e64 v57, v35, v47
	ds_read_b64_tr_b16 v[46:47], v163 offset:16128
	ds_read_b64_tr_b16 v[48:49], v163 offset:17280
	v_cvt_pk_bf16_f32 v34, v34, v35
	v_cvt_pk_bf16_f32 v35, v36, v37
	v_exp_f32_e32 v50, v33
	v_exp_f32_e32 v51, v187
	s_waitcnt lgkmcnt(4)
	v_mfma_f32_32x32x16_bf16 v[0:15], v[64:67], v[38:41], v[0:15]
	s_waitcnt lgkmcnt(2)
	v_mfma_f32_32x32x16_bf16 v[16:31], v[42:45], v[38:41], v[16:31]
	v_add_f32_e64 v42, v36, v56
	v_add_f32_e64 v43, v37, v57
	v_cvt_pk_bf16_f32 v36, v164, v165
	v_cvt_pk_bf16_f32 v37, v168, v169
	v_add_f32_e64 v42, v164, v42
	v_add_f32_e64 v43, v165, v43
	ds_read_b64_tr_b16 v[38:39], v163 offset:16192
	ds_read_b64_tr_b16 v[40:41], v163 offset:17344
	v_pk_add_f32 v[42:43], v[168:169], v[42:43]
	s_waitcnt lgkmcnt(2)
	v_mfma_f32_32x32x16_bf16 v[0:15], v[46:49], v[34:37], v[0:15]
	v_add_f32_e64 v42, v166, v42
	v_add_f32_e64 v43, v167, v43
	v_add_f32_e64 v42, v72, v42
	v_add_f32_e64 v43, v73, v43
	v_add_f32_e64 v46, v74, v42
	v_add_f32_e64 v47, v75, v43
	ds_read_b64_tr_b16 v[42:43], v163 offset:18432
	ds_read_b64_tr_b16 v[44:45], v163 offset:19584
	v_pk_add_f32 v[46:47], v[62:63], v[46:47]
	s_waitcnt lgkmcnt(2)
	v_mfma_f32_32x32x16_bf16 v[16:31], v[38:41], v[34:37], v[16:31]
	v_cvt_pk_bf16_f32 v34, v166, v167
	v_cvt_pk_bf16_f32 v35, v72, v73
	v_cvt_pk_bf16_f32 v36, v74, v75
	v_cvt_pk_bf16_f32 v37, v62, v63
	ds_read_b64_tr_b16 v[38:39], v163 offset:18496
	ds_read_b64_tr_b16 v[40:41], v163 offset:19648
	s_waitcnt lgkmcnt(2)
	v_mfma_f32_32x32x16_bf16 v[0:15], v[42:45], v[34:37], v[0:15]
	v_add_f32_e64 v42, v54, v46
	v_add_f32_e64 v43, v55, v47
	v_add_f32_e64 v42, v60, v42
	v_add_f32_e64 v43, v61, v43
	v_add_f32_e64 v42, v52, v42
	v_add_f32_e64 v43, v53, v43
	v_pk_add_f32 v[42:43], v[50:51], v[42:43]
	s_waitcnt lgkmcnt(0)
	v_mfma_f32_32x32x16_bf16 v[16:31], v[38:41], v[34:37], v[16:31]
	v_add_f32_e32 v33, v42, v43
	ds_bpermute_b32 v34, v238, v33
	ds_read_b64_tr_b16 v[42:43], v163 offset:20736
	ds_read_b64_tr_b16 v[44:45], v163 offset:21888
	ds_read_b64_tr_b16 v[46:47], v163 offset:20800
	ds_read_b64_tr_b16 v[48:49], v163 offset:21952
	v_cvt_pk_bf16_f32 v36, v54, v55
	v_cvt_pk_bf16_f32 v37, v60, v61
	s_waitcnt lgkmcnt(4)
	v_add_f32_e32 v34, v33, v34
	v_div_scale_f32 v33, s[22:23], v34, v34, 1.0
	v_rcp_f32_e32 v35, v33
	v_cvt_pk_bf16_f32 v38, v52, v53
	v_cvt_pk_bf16_f32 v39, v50, v51
	v_add3_u32 v40, v162, v144, v32
	v_ashrrev_i32_e32 v41, 31, v40
	s_waitcnt lgkmcnt(2)
	v_mfma_f32_32x32x16_bf16 v[0:15], v[42:45], v[36:39], v[0:15]
	v_lshlrev_b64 v[40:41], 7, v[40:41]
	s_waitcnt lgkmcnt(0)
	v_mfma_f32_32x32x16_bf16 v[16:31], v[46:49], v[36:39], v[16:31]
	v_fma_f32 v36, -v33, v35, 1.0
	v_fmac_f32_e32 v35, v36, v35
	v_div_scale_f32 v36, vcc, 1.0, v34, 1.0
	v_mul_f32_e32 v37, v36, v35
	v_fma_f32 v38, -v33, v37, v36
	v_fmac_f32_e32 v37, v38, v35
	v_fma_f32 v33, -v33, v37, v36
	v_div_fmas_f32 v33, v33, v35, v37
	v_div_fixup_f32 v36, v33, v34, 1.0
	v_pk_mul_f32 v[0:1], v[36:37], v[0:1] op_sel_hi:[0,1]
	v_pk_mul_f32 v[2:3], v[36:37], v[2:3] op_sel_hi:[0,1]
	v_lshl_add_u64 v[38:39], v[160:161], 0, v[40:41]
	v_cvt_pk_bf16_f32 v0, v0, v1
	v_cvt_pk_bf16_f32 v1, v2, v3
	global_store_dwordx2 v[38:39], v[0:1], off
	v_pk_mul_f32 v[0:1], v[36:37], v[16:17] op_sel_hi:[0,1]
	v_pk_mul_f32 v[2:3], v[36:37], v[18:19] op_sel_hi:[0,1]
	v_cvt_pk_bf16_f32 v0, v0, v1
	v_cvt_pk_bf16_f32 v1, v2, v3
	global_store_dwordx2 v[38:39], v[0:1], off offset:64
	v_pk_mul_f32 v[0:1], v[36:37], v[4:5] op_sel_hi:[0,1]
	v_pk_mul_f32 v[2:3], v[36:37], v[6:7] op_sel_hi:[0,1]
	v_cvt_pk_bf16_f32 v0, v0, v1
	v_cvt_pk_bf16_f32 v1, v2, v3
	global_store_dwordx2 v[38:39], v[0:1], off offset:16
	v_pk_mul_f32 v[0:1], v[36:37], v[20:21] op_sel_hi:[0,1]
	v_pk_mul_f32 v[2:3], v[36:37], v[22:23] op_sel_hi:[0,1]
	v_cvt_pk_bf16_f32 v0, v0, v1
	v_cvt_pk_bf16_f32 v1, v2, v3
	global_store_dwordx2 v[38:39], v[0:1], off offset:80
	v_pk_mul_f32 v[0:1], v[36:37], v[8:9] op_sel_hi:[0,1]
	v_pk_mul_f32 v[2:3], v[36:37], v[10:11] op_sel_hi:[0,1]
	v_cvt_pk_bf16_f32 v0, v0, v1
	v_cvt_pk_bf16_f32 v1, v2, v3
	global_store_dwordx2 v[38:39], v[0:1], off offset:32
	v_pk_mul_f32 v[0:1], v[36:37], v[24:25] op_sel_hi:[0,1]
	v_pk_mul_f32 v[2:3], v[36:37], v[26:27] op_sel_hi:[0,1]
	v_cvt_pk_bf16_f32 v0, v0, v1
	v_cvt_pk_bf16_f32 v1, v2, v3
	global_store_dwordx2 v[38:39], v[0:1], off offset:96
	v_pk_mul_f32 v[0:1], v[36:37], v[12:13] op_sel_hi:[0,1]
	v_pk_mul_f32 v[2:3], v[36:37], v[14:15] op_sel_hi:[0,1]
	v_cvt_pk_bf16_f32 v0, v0, v1
	v_cvt_pk_bf16_f32 v1, v2, v3
	global_store_dwordx2 v[38:39], v[0:1], off offset:48
	v_pk_mul_f32 v[0:1], v[36:37], v[28:29] op_sel_hi:[0,1]
	v_pk_mul_f32 v[2:3], v[36:37], v[30:31] op_sel_hi:[0,1]
	v_cvt_pk_bf16_f32 v0, v0, v1
	v_cvt_pk_bf16_f32 v1, v2, v3
	global_store_dwordx2 v[38:39], v[0:1], off offset:112
	s_and_saveexec_b64 s[22:23], s[6:7]
	s_cbranch_execz .LBB0_303
	v_log_f32_e32 v2, v34
	v_ashrrev_i32_e32 v33, 31, v32
	v_lshl_add_u64 v[0:1], v[32:33], 2, s[80:81]
	v_ashrrev_i32_e32 v163, 31, v162
	v_lshl_add_u64 v[0:1], v[162:163], 2, v[0:1]
	v_lshl_add_u64 v[0:1], v[0:1], 0, v[184:185]
	v_add_f32_e32 v2, v229, v2
	global_store_dword v[0:1], v2, off
